# v47 plus: sample S5 tile loop (spatial blocks) no longer waits for the previous tile's YB store acks (vmcnt(0) moved to the initial-state path and loop entry; wait-state count to the ds_write kept wit
# speedup vs baseline: 1.0025x; 1.0025x over previous
.LBB0_430:
	s_waitcnt vmcnt(2)
	v_mfma_f32_32x32x16_bf16 v[16:31], v[32:35], v[68:71], 0
	s_cmp_ge_u32 s80, s11
	v_add_u32_e32 v158, 32, v102
	s_nop 0
	v_mov_b64_e32 v[134:135], v[126:127]
	v_mov_b64_e32 v[132:133], v[130:131]
	v_mfma_f32_32x32x16_bf16 v[0:15], v[36:39], v[68:71], 0
	s_nop 5
	ds_write_b128 v153, v[16:19]
	ds_write_b128 v153, v[20:23] offset:32
	ds_write_b128 v153, v[24:27] offset:64
	ds_write_b128 v153, v[28:31] offset:96
	s_nop 1
	ds_write_b128 v153, v[0:3] offset:128
	v_mfma_f32_32x32x16_bf16 v[16:31], v[40:43], v[68:71], 0
	ds_write_b128 v153, v[4:7] offset:160
	ds_write_b128 v153, v[8:11] offset:192
	ds_write_b128 v153, v[12:15] offset:224
	s_nop 8
	ds_write_b128 v153, v[16:19] offset:256
	ds_write_b128 v153, v[20:23] offset:288
	ds_write_b128 v153, v[24:27] offset:320
	ds_write_b128 v153, v[28:31] offset:352
	v_mfma_f32_32x32x16_bf16 v[0:15], v[44:47], v[68:71], 0
	s_nop 11
	ds_write_b128 v153, v[0:3] offset:384
	ds_write_b128 v153, v[4:7] offset:416
	ds_write_b128 v153, v[8:11] offset:448
	ds_write_b128 v153, v[12:15] offset:480
	s_cbranch_scc1 .LBB0_432
	v_ashrrev_i32_e32 v107, 31, v106
	v_add_u32_e32 v2, 32, v102
	v_lshlrev_b64 v[0:1], 12, v[106:107]
	v_ashrrev_i32_e32 v3, 31, v2
	v_lshl_add_u64 v[0:1], v[110:111], 0, v[0:1]
	v_lshlrev_b64 v[2:3], 12, v[2:3]
	v_ashrrev_i32_e32 v105, 31, v104
	v_lshl_add_u64 v[2:3], v[112:113], 0, v[2:3]
	global_load_dwordx4 v[68:71], v[0:1], off
	global_load_dwordx2 v[132:133], v[2:3], off
	v_lshlrev_b64 v[0:1], 12, v[104:105]
	v_lshl_add_u64 v[0:1], v[112:113], 0, v[0:1]
	global_load_dwordx2 v[134:135], v[0:1], off
